# attention head loop: 36 masked bias reads hoisted to the top of each head iteration, divergent regions replaced by fmac+cndmask (same arithmetic)
# baseline (speedup 1.0000x reference)
; __device__ __forceinline__ void attn_phase(unsigned char* smem, const Params& P, int layer) {
;     ...
;             f32x4 sc[10]; float mx = sink;
; #pragma unroll
;             for (int tt = 0; tt < 10; ++tt) { const int tl = w + tt, tc = tl < 15 ? tl : 15;
;                 const bf16x8 K0 = *(const bf16x8*)(Kl + (16 * tc + ql) * 72 + q4 * 8), K1 = *(const bf16x8*)(Kl + (16 * tc + ql) * 72 + 32 + q4 * 8);
;                 f32x4 a = {0.f, 0.f, 0.f, 0.f}; a = __builtin_amdgcn_mfma_f32_16x16x32_bf16(K0, Q0, a, 0, 0, 0); a = __builtin_amdgcn_mfma_f32_16x16x32_bf16(K1, Q1, a, 0, 0, 0);
; #pragma unroll
;                 for (int j = 0; j < 4; ++j) { const int dist = ql + 128 - 16 * tt - 4 * q4 - j, kj = 16 * tl + 4 * q4 + j;
;                     const bool valid = (dist >= 0) && (dist < 128) && (tl < 16) && (blk > 0 || kj >= 128);
;                     const float sv = valid ? (a[j] * 0.125f + Bl[g * 128 + (dist & 127)]) : -INFINITY; a[j] = sv; mx = fmaxf(mx, sv); }
;                 sc[tt] = a; }
.LBB0_505:
	v_add_u32_e32 v164, s76, v61
	v_add_u32_e32 v164, 0x11000, v164
	v_mov_b32_e32 v165, 0xff800000
	ds_read_b32 v124, v164 offset:1536
	ds_read_b32 v125, v164 offset:1532
	ds_read_b32 v126, v164 offset:1528
	ds_read_b32 v127, v164 offset:1524
	ds_read_b32 v128, v164 offset:1472
	ds_read_b32 v129, v164 offset:1468
	ds_read_b32 v130, v164 offset:1464
	ds_read_b32 v131, v164 offset:1460
	ds_read_b32 v132, v164 offset:1408
	ds_read_b32 v133, v164 offset:1404
	ds_read_b32 v134, v164 offset:1400
	ds_read_b32 v135, v164 offset:1396
	ds_read_b32 v136, v164 offset:1344
	ds_read_b32 v137, v164 offset:1340
	ds_read_b32 v138, v164 offset:1336
	ds_read_b32 v139, v164 offset:1332
	ds_read_b32 v140, v164 offset:1280
	ds_read_b32 v141, v164 offset:1276
	ds_read_b32 v142, v164 offset:1272
	ds_read_b32 v143, v164 offset:1268
	ds_read_b32 v144, v164 offset:1216
	ds_read_b32 v145, v164 offset:1212
	ds_read_b32 v146, v164 offset:1208
	ds_read_b32 v147, v164 offset:1204
	ds_read_b32 v148, v164 offset:1152
	ds_read_b32 v149, v164 offset:1148
	ds_read_b32 v150, v164 offset:1144
	ds_read_b32 v151, v164 offset:1140
	ds_read_b32 v152, v164 offset:1088
	ds_read_b32 v153, v164 offset:1084
	ds_read_b32 v154, v164 offset:1080
	ds_read_b32 v155, v164 offset:1076
	ds_read_b32 v156, v164 offset:1024
	ds_read_b32 v157, v164 offset:1020
	ds_read_b32 v158, v164 offset:1016
	ds_read_b32 v159, v164 offset:1012
	ds_read_b128 v[24:27], v45
	ds_read_b128 v[72:75], v45 offset:64
	global_load_dword v33, v1, s[96:97]
	v_add_u32_e32 v87, s76, v61
	v_mov_b32_e32 v82, 0xff800000
	s_waitcnt lgkmcnt(1)
	v_mfma_f32_16x16x32_bf16 v[24:27], v[24:27], v[20:23], 0
	s_waitcnt lgkmcnt(0)
	v_mfma_f32_16x16x32_bf16 v[24:27], v[72:75], v[16:19], v[24:27]
	v_mov_b32_e32 v75, 0xff800000
	s_nop 6
	v_fmac_f32_e32 v124, 0x3e000000, v24
	v_cndmask_b32_e64 v82, v165, v124, s[2:3]
	v_fmac_f32_e32 v125, 0x3e000000, v25
	v_cndmask_b32_e64 v75, v165, v125, s[54:55]
	v_mov_b32_e32 v76, 0xff800000
	v_mov_b32_e32 v81, 0xff800000
	v_fmac_f32_e32 v126, 0x3e000000, v26
	v_cndmask_b32_e64 v81, v165, v126, s[64:65]
	v_fmac_f32_e32 v127, 0x3e000000, v27
	v_cndmask_b32_e64 v76, v165, v127, s[74:75]
	ds_read_b128 v[24:27], v47
	ds_read_b128 v[88:91], v47 offset:64
	v_mov_b32_e32 v72, 0xff800000
	v_mov_b32_e32 v80, 0xff800000
	s_waitcnt lgkmcnt(1)
	v_mfma_f32_16x16x32_bf16 v[24:27], v[24:27], v[20:23], 0
	s_waitcnt lgkmcnt(0)
	v_mfma_f32_16x16x32_bf16 v[24:27], v[88:91], v[16:19], v[24:27]
	s_nop 7
	v_fmac_f32_e32 v128, 0x3e000000, v24
	v_cndmask_b32_e64 v80, v165, v128, s[6:7]
	v_fmac_f32_e32 v129, 0x3e000000, v25
	v_cndmask_b32_e64 v72, v165, v129, s[92:93]
	v_mov_b32_e32 v73, 0xff800000
	v_mov_b32_e32 v74, 0xff800000
	v_fmac_f32_e32 v130, 0x3e000000, v26
	v_cndmask_b32_e64 v74, v165, v130, s[8:9]
	v_fmac_f32_e32 v131, 0x3e000000, v27
	v_cndmask_b32_e64 v73, v165, v131, s[10:11]
	ds_read_b128 v[24:27], v48
	ds_read_b128 v[88:91], v48 offset:64
	v_mov_b32_e32 v77, 0xff800000
	v_mov_b32_e32 v78, 0xff800000
	s_waitcnt lgkmcnt(1)
	v_mfma_f32_16x16x32_bf16 v[24:27], v[24:27], v[20:23], 0
	s_waitcnt lgkmcnt(0)
	v_mfma_f32_16x16x32_bf16 v[24:27], v[88:91], v[16:19], v[24:27]
	s_nop 7
	v_fmac_f32_e32 v132, 0x3e000000, v24
	v_cndmask_b32_e64 v78, v165, v132, s[14:15]
	v_fmac_f32_e32 v133, 0x3e000000, v25
	v_cndmask_b32_e64 v77, v165, v133, s[16:17]
	v_mov_b32_e32 v79, 0xff800000
	v_mov_b32_e32 v83, 0xff800000
	v_fmac_f32_e32 v134, 0x3e000000, v26
	v_cndmask_b32_e64 v83, v165, v134, s[18:19]
	v_fmac_f32_e32 v135, 0x3e000000, v27
	v_cndmask_b32_e64 v79, v165, v135, s[20:21]
	ds_read_b128 v[24:27], v49
	ds_read_b128 v[88:91], v49 offset:64
	v_mov_b32_e32 v84, 0xff800000
	v_mov_b32_e32 v85, 0xff800000
	s_waitcnt lgkmcnt(1)
	v_mfma_f32_16x16x32_bf16 v[24:27], v[24:27], v[20:23], 0
	s_waitcnt lgkmcnt(0)
; __device__ __forceinline__ void attn_phase(unsigned char* smem, const Params& P, int layer) {
;     ...
;             for (int tt = 0; tt < 10; ++tt) { const int tl = w + tt, tc = tl < 15 ? tl : 15;
;                 const bf16x8 K0 = *(const bf16x8*)(Kl + (16 * tc + ql) * 72 + q4 * 8), K1 = *(const bf16x8*)(Kl + (16 * tc + ql) * 72 + 32 + q4 * 8);
;                 f32x4 a = {0.f, 0.f, 0.f, 0.f}; a = __builtin_amdgcn_mfma_f32_16x16x32_bf16(K0, Q0, a, 0, 0, 0); a = __builtin_amdgcn_mfma_f32_16x16x32_bf16(K1, Q1, a, 0, 0, 0);
; #pragma unroll
;                 for (int j = 0; j < 4; ++j) { const int dist = ql + 128 - 16 * tt - 4 * q4 - j, kj = 16 * tl + 4 * q4 + j;
;                     const bool valid = (dist >= 0) && (dist < 128) && (tl < 16) && (blk > 0 || kj >= 128);
;                     const float sv = valid ? (a[j] * 0.125f + Bl[g * 128 + (dist & 127)]) : -INFINITY; a[j] = sv; mx = fmaxf(mx, sv); }
;                 sc[tt] = a; }
	v_mfma_f32_16x16x32_bf16 v[24:27], v[88:91], v[16:19], v[24:27]
	s_nop 7
	v_fmac_f32_e32 v136, 0x3e000000, v24
	v_cndmask_b32_e64 v85, v165, v136, s[24:25]
	v_fmac_f32_e32 v137, 0x3e000000, v25
	v_cndmask_b32_e64 v84, v165, v137, s[26:27]
	v_mov_b32_e32 v86, 0xff800000
	v_mov_b32_e32 v88, 0xff800000
	v_fmac_f32_e32 v138, 0x3e000000, v26
	v_cndmask_b32_e64 v88, v165, v138, s[28:29]
	v_fmac_f32_e32 v139, 0x3e000000, v27
	v_cndmask_b32_e64 v86, v165, v139, s[30:31]
	ds_read_b128 v[24:27], v50
	ds_read_b128 v[90:93], v50 offset:64
	v_mov_b32_e32 v89, 0xff800000
	s_waitcnt lgkmcnt(1)
	v_mfma_f32_16x16x32_bf16 v[24:27], v[24:27], v[20:23], 0
	s_waitcnt lgkmcnt(0)
	v_mfma_f32_16x16x32_bf16 v[24:27], v[90:93], v[16:19], v[24:27]
	v_mov_b32_e32 v90, 0xff800000
	s_nop 6
	v_fmac_f32_e32 v140, 0x3e000000, v24
	v_cndmask_b32_e64 v90, v165, v140, s[34:35]
	v_fmac_f32_e32 v141, 0x3e000000, v25
	v_cndmask_b32_e64 v89, v165, v141, s[36:37]
	v_mov_b32_e32 v91, 0xff800000
	v_mov_b32_e32 v92, 0xff800000
	v_fmac_f32_e32 v142, 0x3e000000, v26
	v_cndmask_b32_e64 v92, v165, v142, s[38:39]
	v_fmac_f32_e32 v143, 0x3e000000, v27
	v_cndmask_b32_e64 v91, v165, v143, s[42:43]
	ds_read_b128 v[24:27], v51
	ds_read_b128 v[94:97], v51 offset:64
	v_mov_b32_e32 v93, 0xff800000
	s_waitcnt lgkmcnt(1)
	v_mfma_f32_16x16x32_bf16 v[24:27], v[24:27], v[20:23], 0
	s_waitcnt lgkmcnt(0)
	v_mfma_f32_16x16x32_bf16 v[24:27], v[94:97], v[16:19], v[24:27]
	v_mov_b32_e32 v94, 0xff800000
	s_nop 6
	v_fmac_f32_e32 v144, 0x3e000000, v24
	v_cndmask_b32_e64 v94, v165, v144, s[72:73]
	v_fmac_f32_e32 v145, 0x3e000000, v25
	v_cndmask_b32_e64 v93, v165, v145, s[66:67]
	v_mov_b32_e32 v95, 0xff800000
	v_mov_b32_e32 v96, 0xff800000
	v_fmac_f32_e32 v146, 0x3e000000, v26
	v_cndmask_b32_e64 v96, v165, v146, s[68:69]
	v_fmac_f32_e32 v147, 0x3e000000, v27
	v_cndmask_b32_e64 v95, v165, v147, s[70:71]
	ds_read_b128 v[24:27], v52
	ds_read_b128 v[98:101], v52 offset:64
	v_mov_b32_e32 v97, 0xff800000
	s_waitcnt lgkmcnt(1)
	v_mfma_f32_16x16x32_bf16 v[24:27], v[24:27], v[20:23], 0
	s_waitcnt lgkmcnt(0)
	v_mfma_f32_16x16x32_bf16 v[24:27], v[98:101], v[16:19], v[24:27]
	v_mov_b32_e32 v98, 0xff800000
	s_nop 6
	v_fmac_f32_e32 v148, 0x3e000000, v24
	v_cndmask_b32_e64 v98, v165, v148, s[40:41]
	v_fmac_f32_e32 v149, 0x3e000000, v25
	v_cndmask_b32_e64 v97, v165, v149, s[50:51]
	v_mov_b32_e32 v99, 0xff800000
	v_mov_b32_e32 v100, 0xff800000
	v_fmac_f32_e32 v150, 0x3e000000, v26
	v_cndmask_b32_e64 v100, v165, v150, s[52:53]
	v_fmac_f32_e32 v151, 0x3e000000, v27
	v_cndmask_b32_e64 v99, v165, v151, s[62:63]
	ds_read_b128 v[24:27], v53
	ds_read_b128 v[102:105], v53 offset:64
	v_mov_b32_e32 v101, 0xff800000
	s_waitcnt lgkmcnt(1)
	v_mfma_f32_16x16x32_bf16 v[24:27], v[24:27], v[20:23], 0
	s_waitcnt lgkmcnt(0)
	v_mfma_f32_16x16x32_bf16 v[24:27], v[102:105], v[16:19], v[24:27]
	v_mov_b32_e32 v102, 0xff800000
	s_nop 6
	v_fmac_f32_e32 v152, 0x3e000000, v24
	v_cndmask_b32_e64 v102, v165, v152, s[78:79]
	v_fmac_f32_e32 v153, 0x3e000000, v25
	v_cndmask_b32_e64 v101, v165, v153, s[80:81]
	v_mov_b32_e32 v103, 0xff800000
	v_mov_b32_e32 v104, 0xff800000
	v_fmac_f32_e32 v154, 0x3e000000, v26
	v_cndmask_b32_e64 v104, v165, v154, s[82:83]
	v_fmac_f32_e32 v155, 0x3e000000, v27
	v_cndmask_b32_e64 v103, v165, v155, s[58:59]
	ds_read_b128 v[24:27], v54
	s_waitcnt lgkmcnt(0)
	v_mfma_f32_16x16x32_bf16 v[20:23], v[24:27], v[20:23], 0
	ds_read_b128 v[24:27], v54 offset:64
	s_waitcnt lgkmcnt(0)
	v_mfma_f32_16x16x32_bf16 v[16:19], v[24:27], v[16:19], v[20:23]
	s_nop 4
	v_mov_b32_e32 v20, 0xff800000
	v_mov_b32_e32 v21, 0xff800000
	s_nop 0
	v_fmac_f32_e32 v156, 0x3e000000, v16
	v_cndmask_b32_e64 v21, v165, v156, s[84:85]
	v_fmac_f32_e32 v157, 0x3e000000, v17
	v_cndmask_b32_e64 v20, v165, v157, s[94:95]
	v_mov_b32_e32 v105, 0xff800000
	v_mov_b32_e32 v106, 0xff800000
	v_fmac_f32_e32 v158, 0x3e000000, v18
	v_cndmask_b32_e64 v106, v165, v158, s[12:13]
	v_fmac_f32_e32 v159, 0x3e000000, v19
	v_cndmask_b32_e64 v105, v165, v159, s[22:23]
	s_branch .LBB0_502
